# P3 conv item: adjacent scalar v_mul/v_add pairs of the silu stage merged into v_pk_mul_f32 / v_pk_add_f32 (23 instructions fewer per item)
# baseline (speedup 1.0000x reference)
; __global__ void __launch_bounds__(NT, 2) fwd_kernel(Args args) {
;     ...
;                         int mrow; bool ok;
;                         if (lat) { const int rr = cc + dr - 1, tt = t0 + c6 - 1; ok = (rr >= 0) && (rr < 64) && (tt >= 0) && (tt < 64);
;                             const int rc = rr < 0 ? 0 : (rr > 63 ? 63 : rr), tc = tt < 0 ? 0 : (tt > 63 ? 63 : tt); mrow = bb * SEQ + rc * 64 + tc; }
;                         else { const int tt = cc * 64 + t0 + c6 - 1; ok = (dr == 1) && (tt >= 0) && (tt < 256); const int tc = tt < 0 ? 0 : (tt > 255 ? 255 : tt); mrow = MLAT + bb * CTX + tc; }
;                         v4u xv = *(const v4u*)(PROJ + (size_t)mrow * LDP + PX + ch0);
;                         xv.x = ok ? xv.x : 0u; xv.y = ok ? xv.y : 0u; xv.z = ok ? xv.z : 0u; xv.w = ok ? xv.w : 0u;
;                         xr[dr][c6] = xv;
;                     }
; #pragma unroll
;                 for (int tk = 0; tk < 4; ++tk) {
;                     float acc[8] = {cb0.x, cb0.y, cb0.z, cb0.w, cb1.x, cb1.y, cb1.z, cb1.w};
; #pragma unroll
;                     for (int dr = 0; dr < 3; ++dr)
; #pragma unroll
;                         for (int dc = 0; dc < 3; ++dc) { const v4u xv = xr[dr][tk + dc]; const f32x4 w0 = w[dr * 3 + dc][0], w1 = w[dr * 3 + dc][1];
;                             acc[0] += w0.x * bflo(xv.x); acc[1] += w0.y * bfhi(xv.x); acc[2] += w0.z * bflo(xv.y); acc[3] += w0.w * bfhi(xv.y);
;                             acc[4] += w1.x * bflo(xv.z); acc[5] += w1.y * bfhi(xv.z); acc[6] += w1.z * bflo(xv.w); acc[7] += w1.w * bfhi(xv.w); }
.LBB0_381:
	v_mov_b32_e32 v202, 0xbfb8aa3b
	v_mov_b32_e32 v203, 0xbfb8aa3b
	s_waitcnt vmcnt(1)
	v_cndmask_b32_e64 v185, 0, v142, s[12:13]
	v_cndmask_b32_e64 v182, 0, v145, s[12:13]
	v_cndmask_b32_e64 v145, 0, v140, s[90:91]
	v_cndmask_b32_e64 v140, 0, v141, s[90:91]
	v_cndmask_b32_e64 v141, 0, v94, s[52:53]
	v_cndmask_b32_e64 v142, 0, v97, s[52:53]
	v_cndmask_b32_e64 v94, 0, v91, s[30:31]
	v_cndmask_b32_e64 v91, 0, v92, s[30:31]
	v_cndmask_b32_e64 v92, 0, v88, s[28:29]
	v_cndmask_b32_e64 v88, 0, v89, s[28:29]
	v_cndmask_b32_e64 v89, 0, v82, s[24:25]
	v_cndmask_b32_e64 v97, 0, v83, s[24:25]
	v_mov_b64_e32 v[82:83], s[18:19]
	v_cndmask_b32_e64 v184, 0, v143, s[12:13]
	v_cndmask_b32_e64 v183, 0, v144, s[12:13]
	v_cndmask_b32_e64 v144, 0, v95, s[52:53]
	v_cndmask_b32_e64 v143, 0, v96, s[52:53]
	v_cndmask_b32_e64 v95, 0, v90, s[30:31]
	v_cndmask_b32_e64 v90, 0, v93, s[30:31]
	v_cndmask_b32_e64 v96, 0, v86, s[28:29]
	v_cndmask_b32_e64 v93, 0, v87, s[28:29]
	v_mad_i64_i32 v[82:83], s[4:5], v166, s94, v[82:83]
	v_lshlrev_b64 v[86:87], 1, v[152:153]
	v_lshl_add_u64 v[82:83], v[82:83], 0, v[86:87]
	v_add_co_u32_e32 v82, vcc, s72, v82
	v_cndmask_b32_e64 v181, 0, v98, s[54:55]
	s_nop 0
	v_addc_co_u32_e32 v83, vcc, 0, v83, vcc
	v_cndmask_b32_e64 v180, 0, v99, s[54:55]
	v_cndmask_b32_e64 v98, 0, v84, s[24:25]
	v_cndmask_b32_e64 v99, 0, v85, s[24:25]
	global_load_dwordx4 v[82:85], v[82:83], off
	s_waitcnt vmcnt(1)
	v_cndmask_b32_e64 v171, 0, v148, s[34:35]
	v_cndmask_b32_e64 v170, 0, v149, s[34:35]
	v_lshlrev_b32_e32 v148, 16, v96
	v_and_b32_e32 v149, 0xffff0000, v96
	v_cndmask_b32_e64 v191, 0, v130, s[84:85]
	v_cndmask_b32_e64 v130, 0, v118, s[80:81]
	v_cndmask_b32_e64 v118, 0, v117, s[68:69]
	v_cndmask_b32_e64 v117, 0, v106, s[62:63]
	v_cndmask_b32_e64 v163, 0, v104, s[56:57]
	v_cndmask_b32_e64 v162, 0, v105, s[56:57]
	v_lshlrev_b32_e32 v104, 16, v95
	v_and_b32_e32 v105, 0xffff0000, v95
	v_cndmask_b32_e64 v189, 0, v132, s[84:85]
	v_cndmask_b32_e64 v132, 0, v121, s[80:81]
	v_cndmask_b32_e64 v121, 0, v110, s[66:67]
	v_lshlrev_b32_e32 v194, 16, v117
	v_and_b32_e32 v195, 0xffff0000, v117
	v_cndmask_b32_e64 v160, 0, v127, s[6:7]
	v_cndmask_b32_e64 v127, 0, v114, s[68:69]
	v_lshlrev_b32_e32 v154, 16, v121
	v_and_b32_e32 v155, 0xffff0000, v121
	v_cndmask_b32_e64 v190, 0, v131, s[84:85]
	v_cndmask_b32_e64 v131, 0, v119, s[80:81]
	v_cndmask_b32_e64 v119, 0, v116, s[68:69]
	v_cndmask_b32_e64 v116, 0, v107, s[62:63]
	v_cndmask_b32_e64 v107, 0, v108, s[62:63]
	v_cndmask_b32_e64 v106, 0, v109, s[62:63]
	v_lshlrev_b32_e32 v108, 16, v127
	v_and_b32_e32 v109, 0xffff0000, v127
	v_cndmask_b32_e64 v157, 0, v134, s[88:89]
	v_cndmask_b32_e64 v156, 0, v133, s[84:85]
	v_lshlrev_b32_e32 v198, 16, v191
	v_and_b32_e32 v199, 0xffff0000, v191
	v_cndmask_b32_e64 v187, 0, v138, s[90:91]
	v_cndmask_b32_e64 v186, 0, v139, s[90:91]
	v_cndmask_b32_e64 v139, 0, v136, s[88:89]
	v_cndmask_b32_e64 v188, 0, v137, s[88:89]
	v_cndmask_b32_e64 v161, 0, v126, s[6:7]
	v_cndmask_b32_e64 v175, 0, v124, s[82:83]
	v_cndmask_b32_e64 v174, 0, v125, s[82:83]
	v_cndmask_b32_e64 v133, 0, v120, s[80:81]
	v_cndmask_b32_e64 v126, 0, v115, s[68:69]
	v_cndmask_b32_e64 v120, 0, v111, s[66:67]
	v_cndmask_b32_e64 v111, 0, v112, s[66:67]
	v_cndmask_b32_e64 v110, 0, v113, s[66:67]
	v_lshlrev_b32_e32 v192, 16, v97
	v_and_b32_e32 v193, 0xffff0000, v97
	v_lshlrev_b32_e32 v136, 16, v93
	v_and_b32_e32 v137, 0xffff0000, v93
	v_lshlrev_b32_e32 v124, 16, v92
	v_and_b32_e32 v125, 0xffff0000, v92
	v_lshlrev_b32_e32 v114, 16, v88
	v_and_b32_e32 v115, 0xffff0000, v88
	v_lshlrev_b32_e32 v92, 16, v91
	v_and_b32_e32 v93, 0xffff0000, v91
	v_lshlrev_b32_e32 v88, 16, v90
	v_lshlrev_b32_e32 v96, 16, v119
	v_and_b32_e32 v97, 0xffff0000, v119
	v_and_b32_e32 v91, 0xffff0000, v118
	v_and_b32_e32 v119, 0xffff0000, v156
	v_cndmask_b32_e64 v173, 0, v146, s[34:35]
	v_cndmask_b32_e64 v172, 0, v147, s[34:35]
	v_cndmask_b32_e64 v138, 0, v135, s[88:89]
	v_lshlrev_b32_e32 v146, 16, v120
	v_and_b32_e32 v147, 0xffff0000, v120
	v_lshlrev_b32_e32 v134, 16, v111
	v_and_b32_e32 v135, 0xffff0000, v111
	v_lshlrev_b32_e32 v120, 16, v110
	v_and_b32_e32 v121, 0xffff0000, v110
	v_lshlrev_b32_e32 v110, 16, v187
	v_and_b32_e32 v111, 0xffff0000, v187
	v_lshlrev_b32_e32 v112, 16, v99
	v_and_b32_e32 v113, 0xffff0000, v99
	v_and_b32_e32 v99, 0xffff0000, v94
	v_and_b32_e32 v95, 0xffff0000, v140
	v_cndmask_b32_e64 v177, 0, v122, s[82:83]
	v_cndmask_b32_e64 v176, 0, v123, s[82:83]
	v_lshlrev_b32_e32 v196, 16, v116
	v_and_b32_e32 v197, 0xffff0000, v116
	s_waitcnt vmcnt(0)
; __device__ __forceinline__ unsigned pk2(float lo, float hi) { const f32x2cv v = {lo, hi}; const bf16x2cv b = __builtin_convertvector(v, bf16x2cv); return __builtin_bit_cast(unsigned, b); }
; __device__ __forceinline__ float silu(float x) { return x * __builtin_amdgcn_rcpf(1.0f + __expf(-x)); }
; __global__ void __launch_bounds__(NT, 2) fwd_kernel(Args args) {
;     ...
;                 for (int tk = 0; tk < 4; ++tk) {
;                     float acc[8] = {cb0.x, cb0.y, cb0.z, cb0.w, cb1.x, cb1.y, cb1.z, cb1.w};
; #pragma unroll
;                     for (int dr = 0; dr < 3; ++dr)
; #pragma unroll
;                         for (int dc = 0; dc < 3; ++dc) { const v4u xv = xr[dr][tk + dc]; const f32x4 w0 = w[dr * 3 + dc][0], w1 = w[dr * 3 + dc][1];
;                             acc[0] += w0.x * bflo(xv.x); acc[1] += w0.y * bfhi(xv.x); acc[2] += w0.z * bflo(xv.y); acc[3] += w0.w * bfhi(xv.y);
;                             acc[4] += w1.x * bflo(xv.z); acc[5] += w1.y * bfhi(xv.z); acc[6] += w1.z * bflo(xv.w); acc[7] += w1.w * bfhi(xv.w); }
;                     v4u o; o.x = pk2(silu(acc[0]), silu(acc[1])); o.y = pk2(silu(acc[2]), silu(acc[3])); o.z = pk2(silu(acc[4]), silu(acc[5])); o.w = pk2(silu(acc[6]), silu(acc[7]));
;                     *(v4u*)(XBC + (size_t)(64 * ch + t0 + tk) * 768 + ch0) = o;
	v_cndmask_b32_e64 v169, 0, v82, s[0:1]
	v_cndmask_b32_e64 v168, 0, v83, s[0:1]
	v_lshlrev_b32_e32 v82, 16, v89
	v_and_b32_e32 v83, 0xffff0000, v89
	v_pk_fma_f32 v[82:83], v[42:43], v[82:83], v[78:79]
	v_and_b32_e32 v89, 0xffff0000, v90
	v_pk_fma_f32 v[82:83], v[46:47], v[148:149], v[82:83]
	v_lshlrev_b32_e32 v90, 16, v118
	v_pk_fma_f32 v[82:83], v[50:51], v[104:105], v[82:83]
	v_lshlrev_b32_e32 v118, 16, v156
	v_pk_fma_f32 v[82:83], v[54:55], v[194:195], v[82:83]
	v_lshlrev_b32_e32 v156, 16, v157
	v_pk_fma_f32 v[82:83], v[58:59], v[154:155], v[82:83]
	v_and_b32_e32 v157, 0xffff0000, v157
	v_pk_fma_f32 v[82:83], v[62:63], v[108:109], v[82:83]
	v_cndmask_b32_e64 v167, 0, v84, s[0:1]
	v_pk_fma_f32 v[82:83], v[66:67], v[198:199], v[82:83]
	v_cndmask_b32_e64 v166, 0, v85, s[0:1]
	v_pk_fma_f32 v[82:83], v[70:71], v[156:157], v[82:83]
	v_lshlrev_b32_e32 v84, 16, v98
	v_pk_fma_f32 v[82:83], v[74:75], v[110:111], v[82:83]
	v_and_b32_e32 v85, 0xffff0000, v98
	v_lshlrev_b32_e32 v98, 16, v94
	v_lshlrev_b32_e32 v94, 16, v140
	v_mul_f32_e32 v140, 0xbfb8aa3b, v82
	v_exp_f32_e32 v140, v140
	v_pk_fma_f32 v[84:85], v[2:3], v[84:85], v[38:39]
	v_lshlrev_b32_e32 v122, 16, v107
	v_and_b32_e32 v123, 0xffff0000, v107
	v_add_f32_e32 v140, 1.0, v140
	v_lshlrev_b32_e32 v116, 16, v106
	v_and_b32_e32 v117, 0xffff0000, v106
	v_lshlrev_b32_e32 v106, 16, v186
	v_and_b32_e32 v107, 0xffff0000, v186
	v_rcp_f32_e32 v186, v140
	v_mul_f32_e32 v140, 0xbfb8aa3b, v83
	v_pk_fma_f32 v[84:85], v[6:7], v[124:125], v[84:85]
	v_exp_f32_e32 v140, v140
	v_pk_fma_f32 v[84:85], v[10:11], v[92:93], v[84:85]
	v_cndmask_b32_e64 v159, 0, v128, s[6:7]
	v_pk_fma_f32 v[84:85], v[14:15], v[122:123], v[84:85]
	v_cndmask_b32_e64 v158, 0, v129, s[6:7]
	v_pk_fma_f32 v[84:85], v[18:19], v[134:135], v[84:85]
	v_lshlrev_b32_e32 v128, 16, v189
	v_and_b32_e32 v129, 0xffff0000, v189
	v_pk_fma_f32 v[84:85], v[22:23], v[96:97], v[84:85]
	v_lshlrev_b32_e32 v152, 16, v138
	v_and_b32_e32 v153, 0xffff0000, v138
	v_lshlrev_b32_e32 v138, 16, v139
	v_and_b32_e32 v139, 0xffff0000, v139
	v_add_f32_e32 v140, 1.0, v140
	v_pk_fma_f32 v[84:85], v[26:27], v[128:129], v[84:85]
	v_cndmask_b32_e64 v179, 0, v100, s[54:55]
	v_cndmask_b32_e64 v178, 0, v101, s[54:55]
	v_lshlrev_b32_e32 v100, 16, v145
	v_and_b32_e32 v101, 0xffff0000, v145
	v_rcp_f32_e32 v187, v140
	v_pk_fma_f32 v[84:85], v[30:31], v[138:139], v[84:85]
	v_pk_fma_f32 v[112:113], v[4:5], v[112:113], v[40:41]
	v_pk_fma_f32 v[84:85], v[34:35], v[100:101], v[84:85]
	v_pk_mul_f32 v[82:83], v[82:83], v[186:187]
	v_pk_mul_f32 v[122:123], v[84:85], v[202:203]
	v_exp_f32_e32 v122, v122
	v_exp_f32_e32 v123, v123
	v_pk_fma_f32 v[186:187], v[44:45], v[192:193], v[80:81]
	v_pk_fma_f32 v[112:113], v[8:9], v[114:115], v[112:113]
	v_pk_fma_f32 v[186:187], v[48:49], v[136:137], v[186:187]
	v_pk_fma_f32 v[112:113], v[12:13], v[88:89], v[112:113]
	v_pk_fma_f32 v[186:187], v[52:53], v[98:99], v[186:187]
	v_add_f32_e32 v122, 1.0, v122
	v_pk_fma_f32 v[186:187], v[56:57], v[196:197], v[186:187]
	v_add_f32_e32 v123, 1.0, v123
	v_pk_fma_f32 v[112:113], v[16:17], v[116:117], v[112:113]
	v_cndmask_b32_e64 v165, 0, v102, s[56:57]
	v_cndmask_b32_e64 v164, 0, v103, s[56:57]
	v_lshlrev_b32_e32 v102, 16, v126
	v_and_b32_e32 v103, 0xffff0000, v126
	v_pk_fma_f32 v[186:187], v[60:61], v[146:147], v[186:187]
	v_rcp_f32_e32 v122, v122
	v_rcp_f32_e32 v123, v123
	v_pk_fma_f32 v[112:113], v[20:21], v[120:121], v[112:113]
	v_lshlrev_b32_e32 v200, 16, v190
	v_and_b32_e32 v201, 0xffff0000, v190
	v_pk_fma_f32 v[186:187], v[64:65], v[102:103], v[186:187]
	v_pk_fma_f32 v[112:113], v[24:25], v[90:91], v[112:113]
	v_lshlrev_b32_e32 v126, 16, v188
	v_and_b32_e32 v127, 0xffff0000, v188
	v_pk_fma_f32 v[186:187], v[68:69], v[200:201], v[186:187]
	v_pk_fma_f32 v[112:113], v[28:29], v[118:119], v[112:113]
	v_pk_fma_f32 v[186:187], v[72:73], v[152:153], v[186:187]
	v_pk_fma_f32 v[112:113], v[32:33], v[126:127], v[112:113]
	v_pk_fma_f32 v[186:187], v[76:77], v[106:107], v[186:187]
	v_pk_mul_f32 v[84:85], v[84:85], v[122:123]
	v_pk_fma_f32 v[112:113], v[36:37], v[94:95], v[112:113]
	v_cvt_pk_bf16_f32 v82, v82, v83
	v_mul_f32_e32 v83, 0xbfb8aa3b, v186
	v_cvt_pk_bf16_f32 v84, v84, v85
	v_mul_f32_e32 v85, 0xbfb8aa3b, v112
	v_exp_f32_e32 v83, v83
	v_exp_f32_e32 v85, v85
	v_add_u32_e32 v150, s26, v150
	v_lshl_add_u64 v[86:87], s[20:21], 0, v[86:87]
	v_add_f32_e32 v83, 1.0, v83
	v_add_f32_e32 v85, 1.0, v85
	v_rcp_f32_e32 v188, v83
	v_mul_f32_e32 v83, 0xbfb8aa3b, v187
	v_rcp_f32_e32 v116, v85
	v_mul_f32_e32 v85, 0xbfb8aa3b, v113
	v_exp_f32_e32 v83, v83
	v_exp_f32_e32 v85, v85
	v_pk_fma_f32 v[114:115], v[4:5], v[114:115], v[40:41]
	v_pk_fma_f32 v[148:149], v[42:43], v[148:149], v[78:79]
	v_add_f32_e32 v83, 1.0, v83
	v_add_f32_e32 v85, 1.0, v85
	v_rcp_f32_e32 v189, v83
	v_rcp_f32_e32 v117, v85
	v_pk_fma_f32 v[136:137], v[44:45], v[136:137], v[80:81]
	v_pk_fma_f32 v[124:125], v[2:3], v[124:125], v[38:39]
	v_pk_mul_f32 v[186:187], v[186:187], v[188:189]
	v_pk_mul_f32 v[112:113], v[112:113], v[116:117]
	v_cvt_pk_bf16_f32 v83, v186, v187
	v_cvt_pk_bf16_f32 v85, v112, v113
	v_mad_i64_i32 v[112:113], s[0:1], v150, s96, v[86:87]
	global_store_dwordx4 v[112:113], v[82:85], off sc1
	v_pk_fma_f32 v[114:115], v[8:9], v[88:89], v[114:115]
	v_lshlrev_b32_e32 v140, 16, v141
	v_lshlrev_b32_e32 v82, 16, v142
	v_and_b32_e32 v83, 0xffff0000, v142
	v_and_b32_e32 v141, 0xffff0000, v141
	v_lshlrev_b32_e32 v128, 16, v144
	v_and_b32_e32 v129, 0xffff0000, v144
	v_lshlrev_b32_e32 v116, 16, v143
	v_and_b32_e32 v117, 0xffff0000, v143
	v_pk_fma_f32 v[148:149], v[46:47], v[104:105], v[148:149]
	v_pk_fma_f32 v[136:137], v[48:49], v[98:99], v[136:137]
; __device__ __forceinline__ unsigned pk2(float lo, float hi) { const f32x2cv v = {lo, hi}; const bf16x2cv b = __builtin_convertvector(v, bf16x2cv); return __builtin_bit_cast(unsigned, b); }
; __device__ __forceinline__ float silu(float x) { return x * __builtin_amdgcn_rcpf(1.0f + __expf(-x)); }
; __global__ void __launch_bounds__(NT, 2) fwd_kernel(Args args) {
;     ...
;                 for (int tk = 0; tk < 4; ++tk) {
;                     float acc[8] = {cb0.x, cb0.y, cb0.z, cb0.w, cb1.x, cb1.y, cb1.z, cb1.w};
; #pragma unroll
;                     for (int dr = 0; dr < 3; ++dr)
; #pragma unroll
;                         for (int dc = 0; dc < 3; ++dc) { const v4u xv = xr[dr][tk + dc]; const f32x4 w0 = w[dr * 3 + dc][0], w1 = w[dr * 3 + dc][1];
;                             acc[0] += w0.x * bflo(xv.x); acc[1] += w0.y * bfhi(xv.x); acc[2] += w0.z * bflo(xv.y); acc[3] += w0.w * bfhi(xv.y);
;                             acc[4] += w1.x * bflo(xv.z); acc[5] += w1.y * bfhi(xv.z); acc[6] += w1.z * bflo(xv.w); acc[7] += w1.w * bfhi(xv.w); }
;                     v4u o; o.x = pk2(silu(acc[0]), silu(acc[1])); o.y = pk2(silu(acc[2]), silu(acc[3])); o.z = pk2(silu(acc[4]), silu(acc[5])); o.w = pk2(silu(acc[6]), silu(acc[7]));
;                     *(v4u*)(XBC + (size_t)(64 * ch + t0 + tk) * 768 + ch0) = o;
	v_pk_fma_f32 v[124:125], v[6:7], v[92:93], v[124:125]
	v_pk_fma_f32 v[114:115], v[12:13], v[82:83], v[114:115]
	v_pk_fma_f32 v[148:149], v[50:51], v[140:141], v[148:149]
	v_pk_fma_f32 v[136:137], v[52:53], v[128:129], v[136:137]
	v_pk_fma_f32 v[124:125], v[10:11], v[116:117], v[124:125]
	v_pk_fma_f32 v[114:115], v[16:17], v[120:121], v[114:115]
	v_lshlrev_b32_e32 v84, 16, v132
	v_and_b32_e32 v85, 0xffff0000, v132
	v_pk_fma_f32 v[148:149], v[54:55], v[154:155], v[148:149]
	v_pk_fma_f32 v[136:137], v[56:57], v[146:147], v[136:137]
	v_pk_fma_f32 v[124:125], v[14:15], v[134:135], v[124:125]
	v_pk_fma_f32 v[114:115], v[20:21], v[90:91], v[114:115]
	v_lshlrev_b32_e32 v142, 16, v130
	v_and_b32_e32 v143, 0xffff0000, v130
	v_lshlrev_b32_e32 v130, 16, v131
	v_and_b32_e32 v131, 0xffff0000, v131
	v_lshlrev_b32_e32 v118, 16, v133
	v_and_b32_e32 v119, 0xffff0000, v133
	v_pk_fma_f32 v[148:149], v[58:59], v[108:109], v[148:149]
	v_pk_fma_f32 v[136:137], v[60:61], v[102:103], v[136:137]
	v_pk_fma_f32 v[124:125], v[18:19], v[96:97], v[124:125]
	v_pk_fma_f32 v[114:115], v[24:25], v[84:85], v[114:115]
	v_pk_fma_f32 v[148:149], v[62:63], v[142:143], v[148:149]
	v_pk_fma_f32 v[136:137], v[64:65], v[130:131], v[136:137]
	v_pk_fma_f32 v[124:125], v[22:23], v[118:119], v[124:125]
	v_pk_fma_f32 v[114:115], v[28:29], v[126:127], v[114:115]
	v_lshlrev_b32_e32 v112, 16, v182
	v_and_b32_e32 v113, 0xffff0000, v182
	v_pk_fma_f32 v[148:149], v[66:67], v[156:157], v[148:149]
	v_pk_fma_f32 v[136:137], v[68:69], v[152:153], v[136:137]
	v_pk_fma_f32 v[124:125], v[26:27], v[138:139], v[124:125]
	v_pk_fma_f32 v[114:115], v[32:33], v[94:95], v[114:115]
	v_lshlrev_b32_e32 v144, 16, v185
	v_and_b32_e32 v145, 0xffff0000, v185
	v_lshlrev_b32_e32 v132, 16, v184
	v_and_b32_e32 v133, 0xffff0000, v184
	v_lshlrev_b32_e32 v122, 16, v183
	v_and_b32_e32 v123, 0xffff0000, v183
	v_pk_fma_f32 v[148:149], v[70:71], v[110:111], v[148:149]
	v_pk_fma_f32 v[136:137], v[72:73], v[106:107], v[136:137]
	v_pk_fma_f32 v[124:125], v[30:31], v[100:101], v[124:125]
	v_pk_fma_f32 v[114:115], v[36:37], v[112:113], v[114:115]
	v_pk_fma_f32 v[148:149], v[74:75], v[144:145], v[148:149]
	v_pk_fma_f32 v[136:137], v[76:77], v[132:133], v[136:137]
	v_pk_fma_f32 v[124:125], v[34:35], v[122:123], v[124:125]
	v_pk_mul_f32 v[120:121], v[114:115], v[202:203]
	v_pk_mul_f32 v[154:155], v[148:149], v[202:203]
	v_pk_mul_f32 v[146:147], v[136:137], v[202:203]
	v_pk_mul_f32 v[134:135], v[124:125], v[202:203]
	v_exp_f32_e32 v120, v120
	v_exp_f32_e32 v121, v121
	v_exp_f32_e32 v154, v154
	v_exp_f32_e32 v155, v155
	v_exp_f32_e32 v146, v146
	v_exp_f32_e32 v147, v147
	v_exp_f32_e32 v134, v134
	v_exp_f32_e32 v135, v135
	v_pk_add_f32 v[120:121], v[120:121], 1.0 op_sel_hi:[1,0]
	v_pk_add_f32 v[154:155], v[154:155], 1.0 op_sel_hi:[1,0]
	v_pk_add_f32 v[146:147], v[146:147], 1.0 op_sel_hi:[1,0]
	v_pk_add_f32 v[134:135], v[134:135], 1.0 op_sel_hi:[1,0]
	v_rcp_f32_e32 v120, v120
	v_rcp_f32_e32 v121, v121
	v_rcp_f32_e32 v154, v154
	v_rcp_f32_e32 v155, v155
	v_rcp_f32_e32 v146, v146
	v_rcp_f32_e32 v147, v147
	v_rcp_f32_e32 v134, v134
	v_rcp_f32_e32 v135, v135
	v_pk_mul_f32 v[114:115], v[114:115], v[120:121]
	v_pk_mul_f32 v[148:149], v[148:149], v[154:155]
	v_pk_mul_f32 v[136:137], v[136:137], v[146:147]
	v_pk_mul_f32 v[124:125], v[124:125], v[134:135]
	v_cvt_pk_bf16_f32 v157, v114, v115
	v_or_b32_e32 v114, 1, v150
	v_cvt_pk_bf16_f32 v154, v148, v149
	v_cvt_pk_bf16_f32 v155, v136, v137
	v_cvt_pk_bf16_f32 v156, v124, v125
	v_mad_i64_i32 v[114:115], s[0:1], v114, s96, v[86:87]
	v_pk_fma_f32 v[88:89], v[4:5], v[88:89], v[40:41]
	global_store_dwordx4 v[114:115], v[154:157], off sc1
	v_lshlrev_b32_e32 v114, 16, v178
	v_and_b32_e32 v115, 0xffff0000, v178
	v_pk_fma_f32 v[104:105], v[42:43], v[104:105], v[78:79]
	v_pk_fma_f32 v[98:99], v[44:45], v[98:99], v[80:81]
	v_pk_fma_f32 v[92:93], v[2:3], v[92:93], v[38:39]
	v_pk_fma_f32 v[88:89], v[8:9], v[82:83], v[88:89]
	v_lshlrev_b32_e32 v152, 16, v181
	v_and_b32_e32 v153, 0xffff0000, v181
	v_lshlrev_b32_e32 v138, 16, v180
	v_and_b32_e32 v139, 0xffff0000, v180
	v_lshlrev_b32_e32 v126, 16, v179
	v_and_b32_e32 v127, 0xffff0000, v179
	v_pk_fma_f32 v[104:105], v[46:47], v[140:141], v[104:105]
	v_pk_fma_f32 v[98:99], v[48:49], v[128:129], v[98:99]
	v_pk_fma_f32 v[92:93], v[6:7], v[116:117], v[92:93]
	v_pk_fma_f32 v[88:89], v[12:13], v[114:115], v[88:89]
	v_pk_fma_f32 v[104:105], v[50:51], v[152:153], v[104:105]
	v_pk_fma_f32 v[98:99], v[52:53], v[138:139], v[98:99]
	v_pk_fma_f32 v[92:93], v[10:11], v[126:127], v[92:93]
	v_pk_fma_f32 v[88:89], v[16:17], v[90:91], v[88:89]
	v_lshlrev_b32_e32 v120, 16, v174
	v_and_b32_e32 v121, 0xffff0000, v174
	v_pk_fma_f32 v[104:105], v[54:55], v[108:109], v[104:105]
	v_pk_fma_f32 v[98:99], v[56:57], v[102:103], v[98:99]
	v_pk_fma_f32 v[92:93], v[14:15], v[96:97], v[92:93]
	v_pk_fma_f32 v[88:89], v[20:21], v[84:85], v[88:89]
	v_lshlrev_b32_e32 v154, 16, v177
	v_and_b32_e32 v155, 0xffff0000, v177
	v_lshlrev_b32_e32 v146, 16, v176
	v_and_b32_e32 v147, 0xffff0000, v176
	v_lshlrev_b32_e32 v134, 16, v175
	v_and_b32_e32 v135, 0xffff0000, v175
	v_pk_fma_f32 v[104:105], v[58:59], v[142:143], v[104:105]
	v_pk_fma_f32 v[98:99], v[60:61], v[130:131], v[98:99]
	v_pk_fma_f32 v[92:93], v[18:19], v[118:119], v[92:93]
	v_pk_fma_f32 v[88:89], v[24:25], v[120:121], v[88:89]
	v_pk_fma_f32 v[104:105], v[62:63], v[154:155], v[104:105]
	v_pk_fma_f32 v[98:99], v[64:65], v[146:147], v[98:99]
	v_pk_fma_f32 v[92:93], v[22:23], v[134:135], v[92:93]
	v_pk_fma_f32 v[88:89], v[28:29], v[94:95], v[88:89]
	v_lshlrev_b32_e32 v124, 16, v170
	v_and_b32_e32 v125, 0xffff0000, v170
; __device__ __forceinline__ unsigned pk2(float lo, float hi) { const f32x2cv v = {lo, hi}; const bf16x2cv b = __builtin_convertvector(v, bf16x2cv); return __builtin_bit_cast(unsigned, b); }
; __device__ __forceinline__ float silu(float x) { return x * __builtin_amdgcn_rcpf(1.0f + __expf(-x)); }
; __global__ void __launch_bounds__(NT, 2) fwd_kernel(Args args) {
;     ...
;                 for (int tk = 0; tk < 4; ++tk) {
;                     float acc[8] = {cb0.x, cb0.y, cb0.z, cb0.w, cb1.x, cb1.y, cb1.z, cb1.w};
; #pragma unroll
;                     for (int dr = 0; dr < 3; ++dr)
; #pragma unroll
;                         for (int dc = 0; dc < 3; ++dc) { const v4u xv = xr[dr][tk + dc]; const f32x4 w0 = w[dr * 3 + dc][0], w1 = w[dr * 3 + dc][1];
;                             acc[0] += w0.x * bflo(xv.x); acc[1] += w0.y * bfhi(xv.x); acc[2] += w0.z * bflo(xv.y); acc[3] += w0.w * bfhi(xv.y);
;                             acc[4] += w1.x * bflo(xv.z); acc[5] += w1.y * bfhi(xv.z); acc[6] += w1.z * bflo(xv.w); acc[7] += w1.w * bfhi(xv.w); }
;                     v4u o; o.x = pk2(silu(acc[0]), silu(acc[1])); o.y = pk2(silu(acc[2]), silu(acc[3])); o.z = pk2(silu(acc[4]), silu(acc[5])); o.w = pk2(silu(acc[6]), silu(acc[7]));
;                     *(v4u*)(XBC + (size_t)(64 * ch + t0 + tk) * 768 + ch0) = o;
	v_pk_fma_f32 v[104:105], v[66:67], v[110:111], v[104:105]
	v_pk_fma_f32 v[98:99], v[68:69], v[106:107], v[98:99]
	v_pk_fma_f32 v[92:93], v[26:27], v[100:101], v[92:93]
	v_pk_fma_f32 v[88:89], v[32:33], v[112:113], v[88:89]
	v_lshlrev_b32_e32 v156, 16, v173
	v_and_b32_e32 v157, 0xffff0000, v173
	v_lshlrev_b32_e32 v148, 16, v172
	v_and_b32_e32 v149, 0xffff0000, v172
	v_lshlrev_b32_e32 v136, 16, v171
	v_and_b32_e32 v137, 0xffff0000, v171
	v_pk_fma_f32 v[104:105], v[70:71], v[144:145], v[104:105]
	v_pk_fma_f32 v[98:99], v[72:73], v[132:133], v[98:99]
	v_pk_fma_f32 v[92:93], v[30:31], v[122:123], v[92:93]
	v_pk_fma_f32 v[88:89], v[36:37], v[124:125], v[88:89]
	v_pk_fma_f32 v[104:105], v[74:75], v[156:157], v[104:105]
	v_pk_fma_f32 v[98:99], v[76:77], v[148:149], v[98:99]
	v_pk_fma_f32 v[92:93], v[34:35], v[136:137], v[92:93]
	v_pk_mul_f32 v[90:91], v[88:89], v[202:203]
	v_pk_mul_f32 v[108:109], v[104:105], v[202:203]
	v_pk_mul_f32 v[102:103], v[98:99], v[202:203]
	v_pk_mul_f32 v[96:97], v[92:93], v[202:203]
	v_exp_f32_e32 v90, v90
	v_exp_f32_e32 v91, v91
	v_exp_f32_e32 v108, v108
	v_exp_f32_e32 v109, v109
	v_exp_f32_e32 v102, v102
	v_exp_f32_e32 v103, v103
	v_exp_f32_e32 v96, v96
	v_exp_f32_e32 v97, v97
	v_pk_add_f32 v[90:91], v[90:91], 1.0 op_sel_hi:[1,0]
	v_pk_add_f32 v[108:109], v[108:109], 1.0 op_sel_hi:[1,0]
	v_pk_add_f32 v[102:103], v[102:103], 1.0 op_sel_hi:[1,0]
	v_pk_add_f32 v[96:97], v[96:97], 1.0 op_sel_hi:[1,0]
	v_rcp_f32_e32 v90, v90
	v_rcp_f32_e32 v91, v91
	v_rcp_f32_e32 v108, v108
	v_rcp_f32_e32 v109, v109
	v_rcp_f32_e32 v102, v102
	v_rcp_f32_e32 v103, v103
	v_rcp_f32_e32 v96, v96
	v_rcp_f32_e32 v97, v97
	v_pk_mul_f32 v[88:89], v[88:89], v[90:91]
	v_pk_mul_f32 v[104:105], v[104:105], v[108:109]
	v_pk_mul_f32 v[98:99], v[98:99], v[102:103]
	v_pk_mul_f32 v[92:93], v[92:93], v[96:97]
	v_cvt_pk_bf16_f32 v107, v88, v89
	v_or_b32_e32 v88, 2, v150
	v_cvt_pk_bf16_f32 v104, v104, v105
	v_cvt_pk_bf16_f32 v105, v98, v99
	v_cvt_pk_bf16_f32 v106, v92, v93
	v_mad_i64_i32 v[88:89], s[0:1], v88, s96, v[86:87]
	v_pk_fma_f32 v[42:43], v[42:43], v[140:141], v[78:79]
	global_store_dwordx4 v[88:89], v[104:107], off sc1
	v_lshlrev_b32_e32 v88, 16, v165
	v_and_b32_e32 v89, 0xffff0000, v165
	v_pk_fma_f32 v[42:43], v[46:47], v[152:153], v[42:43]
	v_lshlrev_b32_e32 v96, 16, v161
	v_pk_fma_f32 v[42:43], v[50:51], v[88:89], v[42:43]
	v_and_b32_e32 v97, 0xffff0000, v161
	v_pk_fma_f32 v[42:43], v[54:55], v[142:143], v[42:43]
	v_lshlrev_b32_e32 v104, 16, v169
	v_pk_fma_f32 v[42:43], v[58:59], v[154:155], v[42:43]
	v_and_b32_e32 v105, 0xffff0000, v169
	v_pk_fma_f32 v[42:43], v[62:63], v[96:97], v[42:43]
	v_pk_fma_f32 v[44:45], v[44:45], v[128:129], v[80:81]
	v_pk_fma_f32 v[42:43], v[66:67], v[144:145], v[42:43]
	v_lshlrev_b32_e32 v90, 16, v164
	v_pk_fma_f32 v[42:43], v[70:71], v[156:157], v[42:43]
	v_and_b32_e32 v91, 0xffff0000, v164
	v_pk_fma_f32 v[42:43], v[74:75], v[104:105], v[42:43]
	v_pk_fma_f32 v[44:45], v[48:49], v[138:139], v[44:45]
	v_pk_mul_f32 v[46:47], v[42:43], v[202:203]
	v_exp_f32_e32 v46, v46
	v_exp_f32_e32 v47, v47
	v_pk_fma_f32 v[44:45], v[52:53], v[90:91], v[44:45]
	v_lshlrev_b32_e32 v98, 16, v160
	v_pk_add_f32 v[46:47], v[46:47], 1.0 op_sel_hi:[1,0]
	v_pk_fma_f32 v[44:45], v[56:57], v[130:131], v[44:45]
	v_and_b32_e32 v99, 0xffff0000, v160
	v_rcp_f32_e32 v46, v46
	v_rcp_f32_e32 v47, v47
	v_pk_fma_f32 v[44:45], v[60:61], v[146:147], v[44:45]
	v_pk_fma_f32 v[2:3], v[2:3], v[116:117], v[38:39]
	v_pk_fma_f32 v[44:45], v[64:65], v[98:99], v[44:45]
	v_lshlrev_b32_e32 v92, 16, v163
	v_pk_fma_f32 v[44:45], v[68:69], v[132:133], v[44:45]
	v_and_b32_e32 v93, 0xffff0000, v163
	v_lshlrev_b32_e32 v106, 16, v168
	v_and_b32_e32 v107, 0xffff0000, v168
	v_pk_fma_f32 v[44:45], v[72:73], v[148:149], v[44:45]
	v_pk_fma_f32 v[2:3], v[6:7], v[126:127], v[2:3]
	v_pk_mul_f32 v[42:43], v[42:43], v[46:47]
	v_pk_fma_f32 v[44:45], v[76:77], v[106:107], v[44:45]
	v_pk_fma_f32 v[2:3], v[10:11], v[92:93], v[2:3]
	v_cvt_pk_bf16_f32 v42, v42, v43
	v_mul_f32_e32 v43, 0xbfb8aa3b, v44
	v_pk_fma_f32 v[2:3], v[14:15], v[118:119], v[2:3]
	v_lshlrev_b32_e32 v100, 16, v159
	v_and_b32_e32 v101, 0xffff0000, v159
	v_exp_f32_e32 v43, v43
	v_pk_fma_f32 v[2:3], v[18:19], v[134:135], v[2:3]
	v_lshlrev_b32_e32 v108, 16, v167
	v_pk_fma_f32 v[2:3], v[22:23], v[100:101], v[2:3]
	v_and_b32_e32 v109, 0xffff0000, v167
	v_pk_fma_f32 v[2:3], v[26:27], v[122:123], v[2:3]
	v_add_f32_e32 v43, 1.0, v43
	v_pk_fma_f32 v[2:3], v[30:31], v[136:137], v[2:3]
	v_rcp_f32_e32 v46, v43
	v_pk_fma_f32 v[2:3], v[34:35], v[108:109], v[2:3]
	v_mul_f32_e32 v43, 0xbfb8aa3b, v45
	v_pk_mul_f32 v[6:7], v[2:3], v[202:203]
	v_exp_f32_e32 v43, v43
	v_exp_f32_e32 v6, v6
	v_exp_f32_e32 v7, v7
	v_lshlrev_b32_e32 v94, 16, v162
	v_add_f32_e32 v43, 1.0, v43
	v_pk_add_f32 v[6:7], v[6:7], 1.0 op_sel_hi:[1,0]
	v_rcp_f32_e32 v47, v43
	v_rcp_f32_e32 v6, v6
	v_rcp_f32_e32 v7, v7
	v_and_b32_e32 v95, 0xffff0000, v162
	v_pk_mul_f32 v[44:45], v[44:45], v[46:47]
	v_lshlrev_b32_e32 v102, 16, v158
	v_pk_mul_f32 v[2:3], v[2:3], v[6:7]
	v_cvt_pk_bf16_f32 v43, v44, v45
	v_cvt_pk_bf16_f32 v44, v2, v3
	v_pk_fma_f32 v[2:3], v[4:5], v[82:83], v[40:41]
	v_and_b32_e32 v103, 0xffff0000, v158
	v_pk_fma_f32 v[2:3], v[8:9], v[114:115], v[2:3]
	v_lshlrev_b32_e32 v110, 16, v166
	v_pk_fma_f32 v[2:3], v[12:13], v[94:95], v[2:3]
	v_and_b32_e32 v111, 0xffff0000, v166
	v_pk_fma_f32 v[2:3], v[16:17], v[84:85], v[2:3]
	s_nop 0
	v_pk_fma_f32 v[2:3], v[20:21], v[120:121], v[2:3]
	s_nop 0
	v_pk_fma_f32 v[2:3], v[24:25], v[102:103], v[2:3]
	s_nop 0
	v_pk_fma_f32 v[2:3], v[28:29], v[112:113], v[2:3]
	s_nop 0
	v_pk_fma_f32 v[2:3], v[32:33], v[124:125], v[2:3]
	s_nop 0
	v_pk_fma_f32 v[2:3], v[36:37], v[110:111], v[2:3]
	s_nop 0
	v_pk_mul_f32 v[4:5], v[2:3], v[202:203]
	v_exp_f32_e32 v4, v4
	v_exp_f32_e32 v5, v5
	s_nop 0
	v_pk_add_f32 v[4:5], v[4:5], 1.0 op_sel_hi:[1,0]
	v_rcp_f32_e32 v4, v4
	v_rcp_f32_e32 v5, v5
	s_nop 0
	v_pk_mul_f32 v[2:3], v[2:3], v[4:5]
	s_nop 0
	v_cvt_pk_bf16_f32 v45, v2, v3
	v_or_b32_e32 v2, 3, v150
	v_mad_i64_i32 v[2:3], s[0:1], v2, s96, v[86:87]
	global_store_dwordx4 v[2:3], v[42:45], off sc1
